# write-through (sc1) final-output stores in P6 plus nt weight loads in P0, on top of nt row loads in P1/P6
# speedup vs baseline: 1.0761x; 1.0056x over previous
.Lp6_have:
	s_nop 1
	v_mov_b32_e32 v70, v160
	v_mov_b32_e32 v71, v161
	v_mov_b32_e32 v72, v162
	v_mov_b32_e32 v73, v163
	v_addc_co_u32_e32 v113, vcc, 0, v127, vcc
	s_nop 1
	v_mov_b32_e32 v104, v192
	v_mov_b32_e32 v105, v193
	v_mov_b32_e32 v106, v194
	v_mov_b32_e32 v107, v195
	s_nop 1
	v_mov_b32_e32 v108, v176
	v_mov_b32_e32 v109, v177
	v_mov_b32_e32 v110, v178
	v_mov_b32_e32 v111, v179
	v_add_co_u32_e32 v112, vcc, s22, v126
	v_mov_b32_e32 v128, v77
	s_nop 0
	v_addc_co_u32_e32 v113, vcc, 0, v127, vcc
	s_nop 1
	v_mov_b32_e32 v112, v208
	v_mov_b32_e32 v113, v209
	v_mov_b32_e32 v114, v210
	v_mov_b32_e32 v115, v211
	v_mov_b32_e32 v129, v95
	v_cvt_f32_f16_sdwa v83, v69 dst_sel:DWORD dst_unused:UNUSED_PAD src0_sel:WORD_1
	v_cvt_f32_f16_e32 v82, v69
	v_mov_b32_e32 v68, v76
	v_mov_b32_e32 v69, v94
	v_pk_mul_f32 v[128:129], v[128:129], v[128:129]
	v_add_f32_e32 v67, v122, v123
	v_pk_fma_f32 v[68:69], v[68:69], v[68:69], v[128:129]
	v_mov_b32_e32 v128, v78
	v_mov_b32_e32 v129, v96
	v_pk_fma_f32 v[68:69], v[128:129], v[128:129], v[68:69]
	v_mov_b32_e32 v128, v79
	v_mov_b32_e32 v129, v97
	v_pk_fma_f32 v[68:69], v[128:129], v[128:129], v[68:69]
	v_mov_b32_e32 v122, v81
	v_add_f32_e32 v67, v69, v67
	v_mov_b32_e32 v123, v75
	v_add_f32_e32 v67, v68, v67
	v_mov_b32_e32 v68, v80
	v_mov_b32_e32 v69, v74
	v_pk_mul_f32 v[122:123], v[122:123], v[122:123]
	v_add_f32_dpp v67, v67, v67 row_ror:8 row_mask:0xf bank_mask:0xf bound_ctrl:1
	v_pk_fma_f32 v[68:69], v[68:69], v[68:69], v[122:123]
	v_mov_b32_e32 v122, v82
	v_mov_b32_e32 v123, v84
	v_pk_fma_f32 v[68:69], v[122:123], v[122:123], v[68:69]
	v_mov_b32_e32 v122, v83
	v_mov_b32_e32 v123, v85
	v_pk_fma_f32 v[68:69], v[122:123], v[122:123], v[68:69]
	v_add_f32_e32 v122, v124, v125
	v_add_f32_dpp v67, v67, v67 row_ror:4 row_mask:0xf bank_mask:0xf bound_ctrl:1
	v_add_f32_e32 v69, v69, v122
	v_add_f32_e32 v68, v68, v69
	v_add_f32_dpp v67, v67, v67 row_ror:2 row_mask:0xf bank_mask:0xf bound_ctrl:1
	v_mov_b32_e32 v69, 0
	v_add_f32_dpp v68, v68, v68 row_ror:8 row_mask:0xf bank_mask:0xf bound_ctrl:1
	v_add_f32_dpp v67, v67, v67 row_ror:1 row_mask:0xf bank_mask:0xf bound_ctrl:1
	v_ashrrev_i32_e32 v49, 31, v48
	v_add_f32_dpp v68, v68, v68 row_ror:4 row_mask:0xf bank_mask:0xf bound_ctrl:1
	v_mov_b32_dpp v69, v67 row_bcast:15 row_mask:0xa bank_mask:0xf
	v_add_f32_e32 v67, v67, v69
	v_mov_b32_e32 v69, 0
	v_add_f32_dpp v68, v68, v68 row_ror:2 row_mask:0xf bank_mask:0xf bound_ctrl:1
	v_lshlrev_b64 v[48:49], 12, v[48:49]
	v_mov_b32_dpp v69, v67 row_bcast:31 row_mask:0xc bank_mask:0xf
	v_add_f32_e32 v67, v67, v69
	v_add_f32_dpp v68, v68, v68 row_ror:1 row_mask:0xf bank_mask:0xf bound_ctrl:1
	v_readlane_b32 s0, v67, 63
	v_lshl_add_u64 v[48:49], v[34:35], 0, v[48:49]
	s_add_i32 s11, s11, s20
	v_fma_f32 v67, s0, v103, v102
	v_mul_f32_e32 v69, 0x4b800000, v67
	v_cmp_gt_f32_e32 vcc, s13, v67
	s_add_i32 s10, s10, 1
	s_nop 0
	v_cndmask_b32_e32 v67, v67, v69, vcc
	v_mov_b32_e32 v69, 0
	v_rsq_f32_e32 v67, v67
	s_nop 0
	v_mov_b32_dpp v69, v68 row_bcast:15 row_mask:0xa bank_mask:0xf
	v_add_f32_e32 v68, v68, v69
	v_mov_b32_e32 v69, 0
	s_nop 1
	v_mov_b32_dpp v69, v68 row_bcast:31 row_mask:0xc bank_mask:0xf
	v_add_f32_e32 v68, v68, v69
	s_nop 0
	v_readlane_b32 s0, v68, 63
	s_nop 1
	v_fma_f32 v68, s0, v103, v102
	v_mul_f32_e32 v69, 0x4b800000, v68
	v_cmp_gt_f32_e64 s[0:1], s13, v68
	s_nop 1
	v_cndmask_b32_e64 v68, v68, v69, s[0:1]
	v_rsq_f32_e32 v68, v68
	v_mul_f32_e32 v69, 0x45800000, v67
	v_cndmask_b32_e32 v122, v67, v69, vcc
	v_pk_mul_f32 v[92:93], v[92:93], v[122:123] op_sel_hi:[1,0]
	v_mul_f32_e32 v67, 0x45800000, v68
	v_cndmask_b32_e64 v124, v68, v67, s[0:1]
	v_pk_mul_f32 v[68:69], v[116:117], v[122:123] op_sel_hi:[1,0]
	v_pk_mul_f32 v[116:117], v[118:119], v[122:123] op_sel_hi:[1,0]
	v_pk_mul_f32 v[68:69], v[70:71], v[68:69]
	v_pk_mul_f32 v[72:73], v[72:73], v[116:117]
	v_pk_fma_f32 v[28:29], v[104:105], v[68:69], v[28:29]
	v_pk_mul_f32 v[68:69], v[120:121], v[124:125] op_sel_hi:[1,0]
	v_pk_mul_f32 v[70:71], v[98:99], v[124:125] op_sel_hi:[1,0]
	v_pk_fma_f32 v[30:31], v[106:107], v[72:73], v[30:31]
	v_pk_mul_f32 v[70:71], v[108:109], v[70:71]
	v_pk_mul_f32 v[68:69], v[110:111], v[68:69]
	v_pk_fma_f32 v[28:29], v[112:113], v[70:71], v[28:29]
	v_pk_fma_f32 v[30:31], v[114:115], v[68:69], v[30:31]
	global_store_dwordx4 v[48:49], v[28:31], off sc1
	s_nop 1
	v_mov_b32_e32 v28, v164
	v_mov_b32_e32 v29, v165
	v_mov_b32_e32 v30, v166
	v_mov_b32_e32 v31, v167
	v_lshl_add_u64 v[72:73], v[126:127], 0, s[4:5]
	s_nop 1
	v_mov_b32_e32 v68, v196
	v_mov_b32_e32 v69, v197
	v_mov_b32_e32 v70, v198
	v_mov_b32_e32 v71, v199
	s_nop 1
	v_mov_b32_e32 v104, v180
	v_mov_b32_e32 v105, v181
	v_mov_b32_e32 v106, v182
	v_mov_b32_e32 v107, v183
	v_lshl_add_u64 v[112:113], v[126:127], 0, s[6:7]
	s_nop 1
	v_mov_b32_e32 v108, v212
	v_mov_b32_e32 v109, v213
	v_mov_b32_e32 v110, v214
	v_mov_b32_e32 v111, v215
	v_pk_mul_f32 v[90:91], v[90:91], v[122:123] op_sel_hi:[1,0]
	v_pk_mul_f32 v[74:75], v[74:75], v[124:125] op_sel_hi:[1,0]
	v_pk_mul_f32 v[84:85], v[84:85], v[124:125] op_sel_hi:[1,0]
	v_pk_mul_f32 v[78:79], v[78:79], v[122:123] op_sel_hi:[1,0]
	v_pk_mul_f32 v[76:77], v[76:77], v[122:123] op_sel_hi:[1,0]
	v_pk_mul_f32 v[80:81], v[80:81], v[124:125] op_sel_hi:[1,0]
	v_pk_mul_f32 v[82:83], v[82:83], v[124:125] op_sel_hi:[1,0]
	v_pk_mul_f32 v[28:29], v[90:91], v[28:29]
	v_pk_mul_f32 v[30:31], v[92:93], v[30:31]
	v_pk_fma_f32 v[16:17], v[28:29], v[68:69], v[16:17]
	v_pk_fma_f32 v[18:19], v[30:31], v[70:71], v[18:19]
	v_pk_mul_f32 v[28:29], v[86:87], v[124:125] op_sel_hi:[1,0]
	v_pk_mul_f32 v[30:31], v[88:89], v[124:125] op_sel_hi:[1,0]
	v_pk_mul_f32 v[28:29], v[104:105], v[28:29]
	v_pk_mul_f32 v[30:31], v[106:107], v[30:31]
	v_pk_fma_f32 v[16:17], v[108:109], v[28:29], v[16:17]
	v_pk_fma_f32 v[18:19], v[110:111], v[30:31], v[18:19]
	global_store_dwordx4 v[48:49], v[16:19], off offset:1024 sc1
	s_nop 1
	v_mov_b32_e32 v16, v168
	v_mov_b32_e32 v17, v169
	v_mov_b32_e32 v18, v170
	v_mov_b32_e32 v19, v171
	s_nop 0
	s_nop 1
	v_mov_b32_e32 v28, v184
	v_mov_b32_e32 v29, v185
	v_mov_b32_e32 v30, v186
	v_mov_b32_e32 v31, v187
	s_nop 1
	v_mov_b32_e32 v68, v200
	v_mov_b32_e32 v69, v201
	v_mov_b32_e32 v70, v202
	v_mov_b32_e32 v71, v203
	s_nop 1
	v_mov_b32_e32 v86, v216
	v_mov_b32_e32 v87, v217
	v_mov_b32_e32 v88, v218
	v_mov_b32_e32 v89, v219
	v_pk_mul_f32 v[90:91], v[96:97], v[122:123] op_sel_hi:[1,0]
	v_pk_mul_f32 v[92:93], v[94:95], v[122:123] op_sel_hi:[1,0]
	v_pk_mul_f32 v[18:19], v[90:91], v[18:19]
	v_pk_mul_f32 v[16:17], v[92:93], v[16:17]
	v_pk_mul_f32 v[30:31], v[84:85], v[30:31]
	v_pk_mul_f32 v[28:29], v[74:75], v[28:29]
	v_pk_fma_f32 v[6:7], v[18:19], v[70:71], v[6:7]
	v_pk_fma_f32 v[4:5], v[16:17], v[68:69], v[4:5]
	v_pk_fma_f32 v[6:7], v[30:31], v[88:89], v[6:7]
	v_pk_fma_f32 v[4:5], v[28:29], v[86:87], v[4:5]
	global_store_dwordx4 v[48:49], v[4:7], off offset:2048 sc1
	s_nop 1
	v_mov_b32_e32 v92, v172
	v_mov_b32_e32 v93, v173
	v_mov_b32_e32 v94, v174
	v_mov_b32_e32 v95, v175
	s_nop 1
	v_mov_b32_e32 v96, v188
	v_mov_b32_e32 v97, v189
	v_mov_b32_e32 v98, v190
	v_mov_b32_e32 v99, v191
	s_nop 1
	v_mov_b32_e32 v104, v204
	v_mov_b32_e32 v105, v205
	v_mov_b32_e32 v106, v206
	v_mov_b32_e32 v107, v207
	s_nop 1
	v_mov_b32_e32 v108, v220
	v_mov_b32_e32 v109, v221
	v_mov_b32_e32 v110, v222
	v_mov_b32_e32 v111, v223
	s_waitcnt vmcnt(3)
	v_mov_b64_e32 v[30:31], v[10:11]
	v_mov_b64_e32 v[18:19], v[14:15]
	v_mov_b64_e32 v[4:5], v[20:21]
	v_mov_b64_e32 v[68:69], v[54:55]
	v_mov_b64_e32 v[72:73], v[52:53]
	v_mov_b64_e32 v[84:85], v[64:65]
	v_mov_b64_e32 v[88:89], v[62:63]
	v_mov_b64_e32 v[70:71], v[60:61]
	v_mov_b64_e32 v[74:75], v[58:59]
	v_mov_b64_e32 v[86:87], v[56:57]
	v_mov_b64_e32 v[90:91], v[50:51]
	v_mov_b64_e32 v[28:29], v[8:9]
	v_mov_b64_e32 v[16:17], v[12:13]
	v_mov_b64_e32 v[6:7], v[22:23]
	v_pk_mul_f32 v[76:77], v[76:77], v[92:93]
	v_pk_mul_f32 v[78:79], v[78:79], v[94:95]
	v_pk_mul_f32 v[82:83], v[82:83], v[98:99]
	v_pk_mul_f32 v[80:81], v[80:81], v[96:97]
	v_pk_fma_f32 v[78:79], v[78:79], v[106:107], v[2:3]
	v_pk_fma_f32 v[76:77], v[76:77], v[104:105], v[0:1]
	v_mov_b64_e32 v[0:1], v[24:25]
	v_pk_fma_f32 v[76:77], v[80:81], v[108:109], v[76:77]
	v_pk_fma_f32 v[78:79], v[82:83], v[110:111], v[78:79]
	v_mov_b64_e32 v[2:3], v[26:27]
	global_store_dwordx4 v[48:49], v[76:79], off offset:3072 sc1
	v_mov_b32_e32 v48, v66
	s_andn2_b64 exec, exec, s[2:3]
	s_cbranch_execz .LBB0_1369
